# attention unit prologue: all Q/rope loads issued up front into free VGPRs, counted vmcnt + v_mov_b64 copies at use sites
# baseline (speedup 1.0000x reference)
; __device__ __forceinline__ float bf_lo(unsigned w) { return __uint_as_float(w << 16); }
; __device__ __forceinline__ float bf_hi(unsigned w) { return __uint_as_float(w & 0xffff0000u); }
; __device__ __forceinline__ void attn_unit(const bf16_t* __restrict__ Qb, const unsigned char* __restrict__ Kn, const unsigned char* __restrict__ Vp, const unsigned char* __restrict__ Kp, ...
;     ...
;     const bf16_t* Qw = Qb + (long)(wid * QBLK + r32) * LDQ;
; #pragma unroll
;     for (int s_ = 0; s_ < 2; ++s_) {
;       u32x4 w[4];
; #pragma unroll
;       for (int j = 0; j < 4; ++j) w[j] = *(const u32x4*)(Qw + 64 * s_ + 32 * hi + 8 * j);
;       v8i f;
; #pragma unroll
;       for (int j = 0; j < 4; ++j) { f[2 * j] = (int)pk4_fp8(QC * bf_lo(w[j].x), QC * bf_hi(w[j].x), QC * bf_lo(w[j].y), QC * bf_hi(w[j].y)); f[2 * j + 1] = (int)pk4_fp8(QC * bf_lo(w[j].z), QC * bf_hi(w[j].z), QC * bf_lo(w[j].w), QC * bf_hi(w[j].w)); }
;       qf[s_] = f;
;     }
;     const f32x2* rp = rope + (size_t)(pos0 + wid * QBLK + r32) * 32;
; __global__ void __launch_bounds__(NWAVES * 64, 2) fwd(Args args) {
;     ...
;                 const int sh = u / nqb, qb = u % nqb, sq = sh >> 5, h = sh & 31;
;                 const size_t row_s = (size_t)sq * L, row_q = row_s + (size_t)qb * 256;
;                 att::attn_unit(QB + row_q * NQ + h * 192, KN8 + row_s * 4096 + h * 128, VP + ((size_t)h * (MG / 4) + row_s / 4) * 512, KPE + row_s * 64,
.LBB0_627:
	s_abs_i32 s7, s73
	s_mul_hi_u32 s8, s7, s94
	s_mul_i32 s9, s8, s91
	s_ashr_i32 s2, s73, 31
	s_sub_i32 s7, s7, s9
	s_xor_b32 s2, s2, s93
	s_add_i32 s9, s8, 1
	s_sub_i32 s28, s7, s91
	s_cmp_ge_u32 s7, s91
	s_cselect_b32 s8, s9, s8
	s_cselect_b32 s7, s28, s7
	s_add_i32 s9, s8, 1
	s_cmp_ge_u32 s7, s91
	s_cselect_b32 s7, s9, s8
	s_xor_b32 s7, s7, s2
	s_sub_i32 s2, s7, s2
	s_mul_i32 s7, s2, s89
	s_sub_i32 s28, s73, s7
	s_ashr_i32 s8, s2, 5
	s_ashr_i32 s9, s8, 31
	s_ashr_i32 s29, s28, 31
	s_and_b32 s74, s2, 31
	s_lshl_b64 s[38:39], s[8:9], s90
	s_lshl_b64 s[8:9], s[28:29], 8
	s_add_u32 s50, s38, s8
	s_addc_u32 s51, s39, s9
	s_mul_i32 s2, s51, 0x3000
	s_mul_hi_u32 s7, s50, 0x3000
	s_add_i32 s7, s7, s2
	s_mul_i32 s2, s50, 0x3000
	v_readlane_b32 s8, v255, 6
	s_add_u32 s2, s8, s2
	v_readlane_b32 s8, v255, 4
	s_addc_u32 s7, s8, s7
	s_mul_i32 s8, s74, 0x180
	s_add_u32 s8, s2, s8
	s_addc_u32 s9, s7, 0
	s_lshl_b64 s[76:77], s[38:39], 12
	s_add_u32 s2, s79, s76
	s_addc_u32 s7, s86, s77
	s_lshl_b32 s49, s74, 7
	s_add_u32 s58, s2, s49
	s_addc_u32 s59, s7, 0
	s_lshl_b32 s2, s74, 11
	s_lshr_b64 s[36:37], s[38:39], 2
	s_add_u32 s36, s36, s2
	s_addc_u32 s37, s37, 0
	s_lshl_b64 s[36:37], s[36:37], 9
	s_add_u32 s60, s87, s36
	s_addc_u32 s61, s88, s37
	s_lshl_b64 s[82:83], s[38:39], 6
	v_mov_b32_e32 v28, v226
	s_add_u32 s84, s15, s82
	s_addc_u32 s85, s33, s83
	v_readfirstlane_b32 s7, v28
	s_ashr_i32 s2, s7, 6
	v_mov_b32_e32 v0, 0x7f7f7f7f
	v_and_b32_e32 v220, 31, v28
	s_lshl_b32 s48, s2, 5
	s_movk_i32 s57, 0x3000
	v_or_b32_e32 v2, s48, v220
	v_mov_b64_e32 v[0:1], s[8:9]
	v_mad_i64_i32 v[0:1], s[8:9], v2, s57, v[0:1]
	v_and_b32_e32 v2, 32, v28
	v_lshlrev_b32_e32 v2, 1, v2
	v_lshl_add_u64 v[16:17], v[0:1], 0, v[2:3]
	global_load_dwordx4 v[4:7], v[16:17], off offset:48
	global_load_dwordx4 v[8:11], v[16:17], off offset:32
	global_load_dwordx4 v[12:15], v[16:17], off offset:16
	global_load_dwordx4 v[18:21], v[16:17], off
	v_lshl_or_b32 v60, s28, 8, v220
	v_add_u32_e32 v60, s48, v60
	v_ashrrev_i32_e32 v61, 31, v60
	v_lshlrev_b64 v[60:61], 8, v[60:61]
	v_lshl_add_u64 v[60:61], s[30:31], 0, v[60:61]
	global_load_dwordx4 v[36:39], v[16:17], off offset:176
	global_load_dwordx4 v[40:43], v[16:17], off offset:160
	global_load_dwordx4 v[44:47], v[16:17], off offset:144
	global_load_dwordx4 v[48:51], v[16:17], off offset:128
	global_load_dwordx4 v[64:67], v[0:1], off offset:256
	global_load_dwordx4 v[68:71], v[0:1], off offset:320
	global_load_dwordx4 v[72:75], v[60:61], off offset:48
	global_load_dwordx4 v[76:79], v[60:61], off offset:32
	global_load_dwordx4 v[80:83], v[60:61], off offset:16
	global_load_dwordx4 v[84:87], v[60:61], off
	global_load_dwordx4 v[88:91], v[0:1], off offset:272
	global_load_dwordx4 v[92:95], v[0:1], off offset:336
	global_load_dwordx4 v[96:99], v[60:61], off offset:112
	global_load_dwordx4 v[100:103], v[60:61], off offset:96
	global_load_dwordx4 v[104:107], v[60:61], off offset:80
	global_load_dwordx4 v[108:111], v[60:61], off offset:64
	global_load_dwordx4 v[112:115], v[0:1], off offset:288
	global_load_dwordx4 v[116:119], v[0:1], off offset:352
	global_load_dwordx4 v[120:123], v[60:61], off offset:176
	global_load_dwordx4 v[124:127], v[60:61], off offset:160
	global_load_dwordx4 v[128:131], v[60:61], off offset:144
	global_load_dwordx4 v[132:135], v[60:61], off offset:128
	global_load_dwordx4 v[136:139], v[0:1], off offset:304
	global_load_dwordx4 v[140:143], v[0:1], off offset:368
	global_load_dwordx4 v[144:147], v[60:61], off offset:240
	global_load_dwordx4 v[172:175], v[60:61], off offset:224
	global_load_dwordx4 v[176:179], v[60:61], off offset:208
	global_load_dwordx4 v[180:183], v[60:61], off offset:192
	v_and_b32_e32 v29, 63, v28
	v_cmp_gt_u32_e64 s[36:37], 32, v29
	v_bfe_u32 v55, v28, 3, 3
	s_lshl_b32 s9, s2, 10
	v_lshlrev_b32_e32 v54, 4, v29
	s_add_i32 s8, s9, 0
	s_mov_b32 m0, s8
	s_mov_b64 s[62:63], -1
	s_waitcnt vmcnt(28)
	v_lshlrev_b32_e32 v2, 16, v18
	v_mul_f32_e32 v2, 0x3dd53b94, v2
	v_and_b32_e32 v18, 0xffff0000, v18
	v_mul_f32_e32 v18, 0x3dd53b94, v18
	v_cvt_pk_fp8_f32 v148, v2, v18
	v_lshlrev_b32_e32 v2, 16, v20
	v_mul_f32_e32 v2, 0x3dd53b94, v2
	v_and_b32_e32 v18, 0xffff0000, v20
	v_mul_f32_e32 v18, 0x3dd53b94, v18
	v_cvt_pk_fp8_f32 v149, v2, v18
	v_lshlrev_b32_e32 v2, 16, v12
	v_mul_f32_e32 v2, 0x3dd53b94, v2
	v_and_b32_e32 v12, 0xffff0000, v12
	v_mul_f32_e32 v12, 0x3dd53b94, v12
	v_cvt_pk_fp8_f32 v150, v2, v12
	v_lshlrev_b32_e32 v2, 16, v14
	v_mul_f32_e32 v2, 0x3dd53b94, v2
	v_and_b32_e32 v12, 0xffff0000, v14
	v_mul_f32_e32 v12, 0x3dd53b94, v12
	v_cvt_pk_fp8_f32 v151, v2, v12
	v_lshlrev_b32_e32 v2, 16, v8
	v_and_b32_e32 v8, 0xffff0000, v8
	v_mul_f32_e32 v2, 0x3dd53b94, v2
	v_mul_f32_e32 v8, 0x3dd53b94, v8
	v_cvt_pk_fp8_f32 v152, v2, v8
	v_lshlrev_b32_e32 v2, 16, v10
	v_and_b32_e32 v8, 0xffff0000, v10
	v_mul_f32_e32 v2, 0x3dd53b94, v2
	v_mul_f32_e32 v8, 0x3dd53b94, v8
	v_lshlrev_b32_e32 v22, 16, v19
	v_and_b32_e32 v19, 0xffff0000, v19
	v_lshlrev_b32_e32 v18, 16, v13
	v_and_b32_e32 v13, 0xffff0000, v13
	v_lshlrev_b32_e32 v12, 16, v9
	v_and_b32_e32 v9, 0xffff0000, v9
	v_cvt_pk_fp8_f32 v153, v2, v8
	v_lshlrev_b32_e32 v2, 16, v4
	v_and_b32_e32 v4, 0xffff0000, v4
	v_lshlrev_b32_e32 v8, 16, v5
	v_and_b32_e32 v5, 0xffff0000, v5
	v_mul_f32_e32 v19, 0x3dd53b94, v19
	v_mul_f32_e32 v13, 0x3dd53b94, v13
	v_mul_f32_e32 v9, 0x3dd53b94, v9
	v_mul_f32_e32 v2, 0x3dd53b94, v2
	v_mul_f32_e32 v4, 0x3dd53b94, v4
	v_mul_f32_e32 v5, 0x3dd53b94, v5
	v_cvt_pk_fp8_f32 v154, v2, v4
	v_mul_f32_e32 v22, 0x3dd53b94, v22
	v_cvt_pk_fp8_f32 v148, v22, v19 op_sel:[0,0,1]
	v_lshlrev_b32_e32 v19, 16, v21
	v_mul_f32_e32 v18, 0x3dd53b94, v18
	v_cvt_pk_fp8_f32 v150, v18, v13 op_sel:[0,0,1]
	v_lshlrev_b32_e32 v13, 16, v15
	v_and_b32_e32 v14, 0xffff0000, v15
	v_mul_f32_e32 v12, 0x3dd53b94, v12
	v_cvt_pk_fp8_f32 v152, v12, v9 op_sel:[0,0,1]
	v_lshlrev_b32_e32 v9, 16, v11
	v_and_b32_e32 v10, 0xffff0000, v11
	v_mul_f32_e32 v8, 0x3dd53b94, v8
	v_cvt_pk_fp8_f32 v154, v8, v5 op_sel:[0,0,1]
	v_lshlrev_b32_e32 v2, 16, v6
	v_and_b32_e32 v4, 0xffff0000, v6
	v_lshlrev_b32_e32 v5, 16, v7
	v_and_b32_e32 v6, 0xffff0000, v7
	v_mul_f32_e32 v19, 0x3dd53b94, v19
	v_and_b32_e32 v20, 0xffff0000, v21
	v_mul_f32_e32 v13, 0x3dd53b94, v13
	v_mul_f32_e32 v14, 0x3dd53b94, v14
	v_mul_f32_e32 v9, 0x3dd53b94, v9
	v_mul_f32_e32 v10, 0x3dd53b94, v10
	v_mul_f32_e32 v2, 0x3dd53b94, v2
	v_mul_f32_e32 v4, 0x3dd53b94, v4
	v_mul_f32_e32 v5, 0x3dd53b94, v5
	v_mul_f32_e32 v6, 0x3dd53b94, v6
	v_cvt_pk_fp8_f32 v155, v2, v4
	v_mul_f32_e32 v20, 0x3dd53b94, v20
	v_cvt_pk_fp8_f32 v149, v19, v20 op_sel:[0,0,1]
	v_cvt_pk_fp8_f32 v151, v13, v14 op_sel:[0,0,1]
	v_cvt_pk_fp8_f32 v153, v9, v10 op_sel:[0,0,1]
	v_cvt_pk_fp8_f32 v155, v5, v6 op_sel:[0,0,1]
	s_waitcnt vmcnt(24)
; __device__ __forceinline__ float bf_lo(unsigned w) { return __uint_as_float(w << 16); }
; __device__ __forceinline__ float bf_hi(unsigned w) { return __uint_as_float(w & 0xffff0000u); }
; __device__ __forceinline__ void attn_unit(const bf16_t* __restrict__ Qb, const unsigned char* __restrict__ Kn, const unsigned char* __restrict__ Vp, const unsigned char* __restrict__ Kp, ...
;     ...
;       for (int j = 0; j < 4; ++j) { f[2 * j] = (int)pk4_fp8(QC * bf_lo(w[j].x), QC * bf_hi(w[j].x), QC * bf_lo(w[j].y), QC * bf_hi(w[j].y)); f[2 * j + 1] = (int)pk4_fp8(QC * bf_lo(w[j].z), QC * bf_hi(w[j].z), QC * bf_lo(w[j].w), QC * bf_hi(w[j].w)); }
;       qf[s_] = f;
;     }
;     const f32x2* rp = rope + (size_t)(pos0 + wid * QBLK + r32) * 32;
;     v8i f;
; #pragma unroll
;     for (int j = 0; j < 4; ++j) {
;       const u32x4 xa = *(const u32x4*)(Qw + 128 + 8 * j), xb = *(const u32x4*)(Qw + 160 + 8 * j);
;       float r_[8];
; #pragma unroll
;       for (int e = 0; e < 8; ++e) { const f32x2 cs = rp[8 * j + e];
;         const unsigned wa = e < 2 ? xa.x : e < 4 ? xa.y : e < 6 ? xa.z : xa.w, wb = e < 2 ? xb.x : e < 4 ? xb.y : e < 6 ? xb.z : xb.w;
;         const float x1 = (e & 1) ? bf_hi(wa) : bf_lo(wa), x2 = (e & 1) ? bf_hi(wb) : bf_lo(wb);
;         r_[e] = QC * (hi ? (x1 * cs.y + x2 * cs.x) : (x1 * cs.x - x2 * cs.y)); }
;       f[2 * j] = (int)pk4_fp8(r_[0], r_[1], r_[2], r_[3]); f[2 * j + 1] = (int)pk4_fp8(r_[4], r_[5], r_[6], r_[7]);
	v_mov_b64_e32 v[4:5], v[36:37]
	v_mov_b64_e32 v[6:7], v[38:39]
	v_mov_b64_e32 v[8:9], v[40:41]
	v_mov_b64_e32 v[10:11], v[42:43]
	v_mov_b64_e32 v[12:13], v[44:45]
	v_mov_b64_e32 v[14:15], v[46:47]
	v_mov_b64_e32 v[16:17], v[48:49]
	v_mov_b64_e32 v[18:19], v[50:51]
	v_lshlrev_b32_e32 v2, 16, v16
	v_mul_f32_e32 v2, 0x3dd53b94, v2
	v_and_b32_e32 v16, 0xffff0000, v16
	v_mul_f32_e32 v16, 0x3dd53b94, v16
	v_cvt_pk_fp8_f32 v156, v2, v16
	v_lshlrev_b32_e32 v2, 16, v18
	v_mul_f32_e32 v2, 0x3dd53b94, v2
	v_and_b32_e32 v16, 0xffff0000, v18
	v_mul_f32_e32 v16, 0x3dd53b94, v16
	v_cvt_pk_fp8_f32 v157, v2, v16
	v_lshlrev_b32_e32 v2, 16, v12
	v_mul_f32_e32 v2, 0x3dd53b94, v2
	v_and_b32_e32 v12, 0xffff0000, v12
	v_mul_f32_e32 v12, 0x3dd53b94, v12
	v_cvt_pk_fp8_f32 v158, v2, v12
	v_lshlrev_b32_e32 v2, 16, v14
	v_mul_f32_e32 v2, 0x3dd53b94, v2
	v_and_b32_e32 v12, 0xffff0000, v14
	v_mul_f32_e32 v12, 0x3dd53b94, v12
	v_cvt_pk_fp8_f32 v159, v2, v12
	v_lshlrev_b32_e32 v2, 16, v8
	v_mul_f32_e32 v2, 0x3dd53b94, v2
	v_and_b32_e32 v8, 0xffff0000, v8
	v_mul_f32_e32 v8, 0x3dd53b94, v8
	v_cvt_pk_fp8_f32 v160, v2, v8
	v_lshlrev_b32_e32 v2, 16, v10
	v_mul_f32_e32 v2, 0x3dd53b94, v2
	v_and_b32_e32 v8, 0xffff0000, v10
	v_mul_f32_e32 v8, 0x3dd53b94, v8
	v_cvt_pk_fp8_f32 v161, v2, v8
	v_lshlrev_b32_e32 v2, 16, v4
	v_mul_f32_e32 v2, 0x3dd53b94, v2
	v_and_b32_e32 v4, 0xffff0000, v4
	v_mul_f32_e32 v4, 0x3dd53b94, v4
	v_lshlrev_b32_e32 v8, 16, v5
	v_and_b32_e32 v5, 0xffff0000, v5
	v_cvt_pk_fp8_f32 v162, v2, v4
	v_lshlrev_b32_e32 v2, 16, v6
	v_mul_f32_e32 v5, 0x3dd53b94, v5
	v_mul_f32_e32 v2, 0x3dd53b94, v2
	v_and_b32_e32 v4, 0xffff0000, v6
	v_lshlrev_b32_e32 v20, 16, v17
	v_and_b32_e32 v17, 0xffff0000, v17
	v_lshlrev_b32_e32 v16, 16, v13
	v_and_b32_e32 v13, 0xffff0000, v13
	v_lshlrev_b32_e32 v12, 16, v9
	v_and_b32_e32 v9, 0xffff0000, v9
	v_mul_f32_e32 v8, 0x3dd53b94, v8
	v_cvt_pk_fp8_f32 v162, v8, v5 op_sel:[0,0,1]
	v_mul_f32_e32 v4, 0x3dd53b94, v4
	v_lshlrev_b32_e32 v5, 16, v7
	v_cvt_pk_fp8_f32 v163, v2, v4
	v_lshl_or_b32 v2, s28, 8, v220
	v_mul_f32_e32 v17, 0x3dd53b94, v17
	v_mul_f32_e32 v13, 0x3dd53b94, v13
	v_mul_f32_e32 v9, 0x3dd53b94, v9
	v_mul_f32_e32 v5, 0x3dd53b94, v5
	v_and_b32_e32 v6, 0xffff0000, v7
	v_add_u32_e32 v4, s48, v2
	v_mul_f32_e32 v20, 0x3dd53b94, v20
	v_cvt_pk_fp8_f32 v156, v20, v17 op_sel:[0,0,1]
	v_lshlrev_b32_e32 v17, 16, v19
	v_and_b32_e32 v18, 0xffff0000, v19
	v_mul_f32_e32 v16, 0x3dd53b94, v16
	v_cvt_pk_fp8_f32 v158, v16, v13 op_sel:[0,0,1]
	v_lshlrev_b32_e32 v13, 16, v15
	v_and_b32_e32 v14, 0xffff0000, v15
	v_mul_f32_e32 v12, 0x3dd53b94, v12
	v_cvt_pk_fp8_f32 v160, v12, v9 op_sel:[0,0,1]
	v_lshlrev_b32_e32 v9, 16, v11
	v_and_b32_e32 v10, 0xffff0000, v11
	v_mul_f32_e32 v6, 0x3dd53b94, v6
	v_cvt_pk_fp8_f32 v163, v5, v6 op_sel:[0,0,1]
	v_ashrrev_i32_e32 v5, 31, v4
	v_mul_f32_e32 v17, 0x3dd53b94, v17
	v_mul_f32_e32 v18, 0x3dd53b94, v18
	v_mul_f32_e32 v13, 0x3dd53b94, v13
	v_mul_f32_e32 v14, 0x3dd53b94, v14
	v_mul_f32_e32 v9, 0x3dd53b94, v9
	v_mul_f32_e32 v10, 0x3dd53b94, v10
	v_lshlrev_b64 v[4:5], 8, v[4:5]
	v_cvt_pk_fp8_f32 v157, v17, v18 op_sel:[0,0,1]
	v_cvt_pk_fp8_f32 v159, v13, v14 op_sel:[0,0,1]
	v_cvt_pk_fp8_f32 v161, v9, v10 op_sel:[0,0,1]
	v_lshl_add_u64 v[24:25], s[30:31], 0, v[4:5]
	s_waitcnt vmcnt(18)
	v_mov_b64_e32 v[4:5], v[64:65]
	v_mov_b64_e32 v[6:7], v[66:67]
	v_mov_b64_e32 v[8:9], v[68:69]
	v_mov_b64_e32 v[10:11], v[70:71]
	v_mov_b64_e32 v[12:13], v[72:73]
	v_mov_b64_e32 v[14:15], v[74:75]
	v_mov_b64_e32 v[16:17], v[76:77]
	v_mov_b64_e32 v[18:19], v[78:79]
	v_mov_b64_e32 v[20:21], v[80:81]
	v_mov_b64_e32 v[22:23], v[82:83]
	v_mov_b64_e32 v[30:31], v[84:85]
	v_mov_b64_e32 v[32:33], v[86:87]
	v_lshlrev_b32_e32 v26, 16, v4
	v_lshlrev_b32_e32 v27, 16, v8
	v_pk_mul_f32 v[34:35], v[30:31], v[26:27] op_sel:[1,0] op_sel_hi:[0,1]
	v_pk_mul_f32 v[26:27], v[30:31], v[26:27]
	v_add_f32_e32 v2, v34, v35
	v_sub_f32_e32 v26, v26, v27
	v_cndmask_b32_e64 v2, v2, v26, s[36:37]
	v_and_b32_e32 v27, 0xffff0000, v8
	v_and_b32_e32 v26, 0xffff0000, v4
	v_pk_mul_f32 v[30:31], v[32:33], v[26:27] op_sel:[1,0] op_sel_hi:[0,1]
	v_pk_mul_f32 v[26:27], v[32:33], v[26:27]
	v_add_f32_e32 v4, v30, v31
	v_sub_f32_e32 v8, v26, v27
	v_lshlrev_b32_e32 v27, 16, v9
	v_lshlrev_b32_e32 v26, 16, v5
	v_cndmask_b32_e64 v4, v4, v8, s[36:37]
	v_pk_mul_f32 v[30:31], v[20:21], v[26:27] op_sel:[1,0] op_sel_hi:[0,1]
	v_pk_mul_f32 v[20:21], v[20:21], v[26:27]
	v_mul_f32_e32 v32, 0x3dd53b94, v4
	v_add_f32_e32 v4, v30, v31
	v_sub_f32_e32 v8, v20, v21
	v_cndmask_b32_e64 v4, v4, v8, s[36:37]
	v_and_b32_e32 v9, 0xffff0000, v9
	v_and_b32_e32 v8, 0xffff0000, v5
	v_mul_f32_e32 v20, 0x3dd53b94, v4
	v_pk_mul_f32 v[4:5], v[22:23], v[8:9] op_sel:[1,0] op_sel_hi:[0,1]
	v_add_f32_e32 v21, v4, v5
	v_pk_mul_f32 v[4:5], v[22:23], v[8:9]
	v_mul_f32_e32 v2, 0x3dd53b94, v2
	v_sub_f32_e32 v4, v4, v5
	v_cndmask_b32_e64 v4, v21, v4, s[36:37]
	v_mul_f32_e32 v21, 0x3dd53b94, v4
	v_lshlrev_b32_e32 v5, 16, v10
	v_lshlrev_b32_e32 v4, 16, v6
	v_pk_mul_f32 v[8:9], v[16:17], v[4:5] op_sel:[1,0] op_sel_hi:[0,1]
	v_pk_mul_f32 v[4:5], v[16:17], v[4:5]
	v_add_f32_e32 v8, v8, v9
	v_sub_f32_e32 v4, v4, v5
	v_cndmask_b32_e64 v4, v8, v4, s[36:37]
	v_mul_f32_e32 v16, 0x3dd53b94, v4
	v_and_b32_e32 v5, 0xffff0000, v10
	v_and_b32_e32 v4, 0xffff0000, v6
	v_pk_mul_f32 v[8:9], v[18:19], v[4:5] op_sel:[1,0] op_sel_hi:[0,1]
	v_pk_mul_f32 v[4:5], v[18:19], v[4:5]
	v_add_f32_e32 v6, v8, v9
	v_sub_f32_e32 v4, v4, v5
	v_cndmask_b32_e64 v4, v6, v4, s[36:37]
	v_mul_f32_e32 v10, 0x3dd53b94, v4
	v_lshlrev_b32_e32 v5, 16, v11
	v_lshlrev_b32_e32 v4, 16, v7
	v_pk_mul_f32 v[8:9], v[12:13], v[4:5] op_sel:[1,0] op_sel_hi:[0,1]
	v_pk_mul_f32 v[4:5], v[12:13], v[4:5]
	v_add_f32_e32 v6, v8, v9
	v_sub_f32_e32 v4, v4, v5
	v_cndmask_b32_e64 v4, v6, v4, s[36:37]
	v_mul_f32_e32 v8, 0x3dd53b94, v4
	v_and_b32_e32 v5, 0xffff0000, v11
	v_and_b32_e32 v4, 0xffff0000, v7
	v_pk_mul_f32 v[6:7], v[14:15], v[4:5] op_sel:[1,0] op_sel_hi:[0,1]
	v_pk_mul_f32 v[4:5], v[14:15], v[4:5]
	v_add_f32_e32 v6, v6, v7
	v_sub_f32_e32 v4, v4, v5
	v_cndmask_b32_e64 v4, v6, v4, s[36:37]
	v_mul_f32_e32 v4, 0x3dd53b94, v4
	v_cvt_pk_fp8_f32 v164, v2, v32
	v_cvt_pk_fp8_f32 v165, v16, v10
	s_nop 0
	v_cvt_pk_fp8_f32 v164, v20, v21 op_sel:[0,0,1]
	v_cvt_pk_fp8_f32 v165, v8, v4 op_sel:[0,0,1]
	s_waitcnt vmcnt(12)
; __device__ __forceinline__ float bf_lo(unsigned w) { return __uint_as_float(w << 16); }
; __device__ __forceinline__ float bf_hi(unsigned w) { return __uint_as_float(w & 0xffff0000u); }
; __device__ __forceinline__ void attn_unit(const bf16_t* __restrict__ Qb, const unsigned char* __restrict__ Kn, const unsigned char* __restrict__ Vp, const unsigned char* __restrict__ Kp, ...
;     ...
;     for (int j = 0; j < 4; ++j) {
;       const u32x4 xa = *(const u32x4*)(Qw + 128 + 8 * j), xb = *(const u32x4*)(Qw + 160 + 8 * j);
;       float r_[8];
; #pragma unroll
;       for (int e = 0; e < 8; ++e) { const f32x2 cs = rp[8 * j + e];
;         const unsigned wa = e < 2 ? xa.x : e < 4 ? xa.y : e < 6 ? xa.z : xa.w, wb = e < 2 ? xb.x : e < 4 ? xb.y : e < 6 ? xb.z : xb.w;
;         const float x1 = (e & 1) ? bf_hi(wa) : bf_lo(wa), x2 = (e & 1) ? bf_hi(wb) : bf_lo(wb);
;         r_[e] = QC * (hi ? (x1 * cs.y + x2 * cs.x) : (x1 * cs.x - x2 * cs.y)); }
;       f[2 * j] = (int)pk4_fp8(r_[0], r_[1], r_[2], r_[3]); f[2 * j + 1] = (int)pk4_fp8(r_[4], r_[5], r_[6], r_[7]);
	v_mov_b64_e32 v[4:5], v[88:89]
	v_mov_b64_e32 v[6:7], v[90:91]
	v_mov_b64_e32 v[8:9], v[92:93]
	v_mov_b64_e32 v[10:11], v[94:95]
	v_mov_b64_e32 v[12:13], v[96:97]
	v_mov_b64_e32 v[14:15], v[98:99]
	v_mov_b64_e32 v[16:17], v[100:101]
	v_mov_b64_e32 v[18:19], v[102:103]
	v_mov_b64_e32 v[20:21], v[104:105]
	v_mov_b64_e32 v[22:23], v[106:107]
	v_mov_b64_e32 v[30:31], v[108:109]
	v_mov_b64_e32 v[32:33], v[110:111]
	v_lshlrev_b32_e32 v26, 16, v4
	v_lshlrev_b32_e32 v27, 16, v8
	v_pk_mul_f32 v[34:35], v[30:31], v[26:27] op_sel:[1,0] op_sel_hi:[0,1]
	v_pk_mul_f32 v[26:27], v[30:31], v[26:27]
	v_add_f32_e32 v2, v34, v35
	v_sub_f32_e32 v26, v26, v27
	v_cndmask_b32_e64 v2, v2, v26, s[36:37]
	v_and_b32_e32 v27, 0xffff0000, v8
	v_and_b32_e32 v26, 0xffff0000, v4
	v_pk_mul_f32 v[30:31], v[32:33], v[26:27] op_sel:[1,0] op_sel_hi:[0,1]
	v_pk_mul_f32 v[26:27], v[32:33], v[26:27]
	v_add_f32_e32 v4, v30, v31
	v_sub_f32_e32 v8, v26, v27
	v_lshlrev_b32_e32 v27, 16, v9
	v_lshlrev_b32_e32 v26, 16, v5
	v_cndmask_b32_e64 v4, v4, v8, s[36:37]
	v_pk_mul_f32 v[30:31], v[20:21], v[26:27] op_sel:[1,0] op_sel_hi:[0,1]
	v_pk_mul_f32 v[20:21], v[20:21], v[26:27]
	v_mul_f32_e32 v32, 0x3dd53b94, v4
	v_add_f32_e32 v4, v30, v31
	v_sub_f32_e32 v8, v20, v21
	v_cndmask_b32_e64 v4, v4, v8, s[36:37]
	v_and_b32_e32 v9, 0xffff0000, v9
	v_and_b32_e32 v8, 0xffff0000, v5
	v_mul_f32_e32 v20, 0x3dd53b94, v4
	v_pk_mul_f32 v[4:5], v[22:23], v[8:9] op_sel:[1,0] op_sel_hi:[0,1]
	v_add_f32_e32 v21, v4, v5
	v_pk_mul_f32 v[4:5], v[22:23], v[8:9]
	v_mul_f32_e32 v2, 0x3dd53b94, v2
	v_sub_f32_e32 v4, v4, v5
	v_cndmask_b32_e64 v4, v21, v4, s[36:37]
	v_mul_f32_e32 v21, 0x3dd53b94, v4
	v_lshlrev_b32_e32 v5, 16, v10
	v_lshlrev_b32_e32 v4, 16, v6
	v_pk_mul_f32 v[8:9], v[16:17], v[4:5] op_sel:[1,0] op_sel_hi:[0,1]
	v_pk_mul_f32 v[4:5], v[16:17], v[4:5]
	v_add_f32_e32 v8, v8, v9
	v_sub_f32_e32 v4, v4, v5
	v_cndmask_b32_e64 v4, v8, v4, s[36:37]
	v_mul_f32_e32 v16, 0x3dd53b94, v4
	v_and_b32_e32 v5, 0xffff0000, v10
	v_and_b32_e32 v4, 0xffff0000, v6
	v_pk_mul_f32 v[8:9], v[18:19], v[4:5] op_sel:[1,0] op_sel_hi:[0,1]
	v_pk_mul_f32 v[4:5], v[18:19], v[4:5]
	v_add_f32_e32 v6, v8, v9
	v_sub_f32_e32 v4, v4, v5
	v_cndmask_b32_e64 v4, v6, v4, s[36:37]
	v_mul_f32_e32 v10, 0x3dd53b94, v4
	v_lshlrev_b32_e32 v5, 16, v11
	v_lshlrev_b32_e32 v4, 16, v7
	v_pk_mul_f32 v[8:9], v[12:13], v[4:5] op_sel:[1,0] op_sel_hi:[0,1]
	v_pk_mul_f32 v[4:5], v[12:13], v[4:5]
	v_add_f32_e32 v6, v8, v9
	v_sub_f32_e32 v4, v4, v5
	v_cndmask_b32_e64 v4, v6, v4, s[36:37]
	v_mul_f32_e32 v8, 0x3dd53b94, v4
	v_and_b32_e32 v5, 0xffff0000, v11
	v_and_b32_e32 v4, 0xffff0000, v7
	v_pk_mul_f32 v[6:7], v[14:15], v[4:5] op_sel:[1,0] op_sel_hi:[0,1]
	v_pk_mul_f32 v[4:5], v[14:15], v[4:5]
	v_add_f32_e32 v6, v6, v7
	v_sub_f32_e32 v4, v4, v5
	v_cndmask_b32_e64 v4, v6, v4, s[36:37]
	v_mul_f32_e32 v4, 0x3dd53b94, v4
	v_cvt_pk_fp8_f32 v166, v2, v32
	v_cvt_pk_fp8_f32 v167, v16, v10
	s_nop 0
	v_cvt_pk_fp8_f32 v166, v20, v21 op_sel:[0,0,1]
	v_cvt_pk_fp8_f32 v167, v8, v4 op_sel:[0,0,1]
	s_waitcnt vmcnt(6)
	v_mov_b64_e32 v[4:5], v[112:113]
	v_mov_b64_e32 v[6:7], v[114:115]
	v_mov_b64_e32 v[8:9], v[116:117]
	v_mov_b64_e32 v[10:11], v[118:119]
	v_mov_b64_e32 v[12:13], v[120:121]
	v_mov_b64_e32 v[14:15], v[122:123]
	v_mov_b64_e32 v[16:17], v[124:125]
	v_mov_b64_e32 v[18:19], v[126:127]
	v_mov_b64_e32 v[20:21], v[128:129]
	v_mov_b64_e32 v[22:23], v[130:131]
	v_mov_b64_e32 v[30:31], v[132:133]
	v_mov_b64_e32 v[32:33], v[134:135]
	v_lshlrev_b32_e32 v26, 16, v4
	v_lshlrev_b32_e32 v27, 16, v8
	v_pk_mul_f32 v[34:35], v[30:31], v[26:27] op_sel:[1,0] op_sel_hi:[0,1]
	v_pk_mul_f32 v[26:27], v[30:31], v[26:27]
	v_add_f32_e32 v2, v34, v35
	v_sub_f32_e32 v26, v26, v27
	v_cndmask_b32_e64 v2, v2, v26, s[36:37]
	v_and_b32_e32 v27, 0xffff0000, v8
	v_and_b32_e32 v26, 0xffff0000, v4
	v_pk_mul_f32 v[30:31], v[32:33], v[26:27] op_sel:[1,0] op_sel_hi:[0,1]
	v_pk_mul_f32 v[26:27], v[32:33], v[26:27]
	v_add_f32_e32 v4, v30, v31
	v_sub_f32_e32 v8, v26, v27
	v_lshlrev_b32_e32 v27, 16, v9
	v_lshlrev_b32_e32 v26, 16, v5
	v_cndmask_b32_e64 v4, v4, v8, s[36:37]
	v_pk_mul_f32 v[30:31], v[20:21], v[26:27] op_sel:[1,0] op_sel_hi:[0,1]
	v_pk_mul_f32 v[20:21], v[20:21], v[26:27]
	v_mul_f32_e32 v32, 0x3dd53b94, v4
	v_add_f32_e32 v4, v30, v31
	v_sub_f32_e32 v8, v20, v21
	v_cndmask_b32_e64 v4, v4, v8, s[36:37]
	v_and_b32_e32 v9, 0xffff0000, v9
	v_and_b32_e32 v8, 0xffff0000, v5
	v_mul_f32_e32 v20, 0x3dd53b94, v4
	v_pk_mul_f32 v[4:5], v[22:23], v[8:9] op_sel:[1,0] op_sel_hi:[0,1]
	v_add_f32_e32 v21, v4, v5
	v_pk_mul_f32 v[4:5], v[22:23], v[8:9]
	v_mul_f32_e32 v2, 0x3dd53b94, v2
	v_sub_f32_e32 v4, v4, v5
	v_cndmask_b32_e64 v4, v21, v4, s[36:37]
	v_mul_f32_e32 v21, 0x3dd53b94, v4
	v_lshlrev_b32_e32 v5, 16, v10
	v_lshlrev_b32_e32 v4, 16, v6
	v_pk_mul_f32 v[8:9], v[16:17], v[4:5] op_sel:[1,0] op_sel_hi:[0,1]
	v_pk_mul_f32 v[4:5], v[16:17], v[4:5]
	v_add_f32_e32 v8, v8, v9
	v_sub_f32_e32 v4, v4, v5
	v_cndmask_b32_e64 v4, v8, v4, s[36:37]
	v_mul_f32_e32 v16, 0x3dd53b94, v4
	v_and_b32_e32 v5, 0xffff0000, v10
	v_and_b32_e32 v4, 0xffff0000, v6
	v_pk_mul_f32 v[8:9], v[18:19], v[4:5] op_sel:[1,0] op_sel_hi:[0,1]
	v_pk_mul_f32 v[4:5], v[18:19], v[4:5]
	v_add_f32_e32 v6, v8, v9
	v_sub_f32_e32 v4, v4, v5
	v_cndmask_b32_e64 v4, v6, v4, s[36:37]
	v_mul_f32_e32 v10, 0x3dd53b94, v4
	v_lshlrev_b32_e32 v5, 16, v11
	v_lshlrev_b32_e32 v4, 16, v7
	v_pk_mul_f32 v[8:9], v[12:13], v[4:5] op_sel:[1,0] op_sel_hi:[0,1]
	v_pk_mul_f32 v[4:5], v[12:13], v[4:5]
	v_add_f32_e32 v6, v8, v9
	v_sub_f32_e32 v4, v4, v5
	v_cndmask_b32_e64 v4, v6, v4, s[36:37]
	v_mul_f32_e32 v8, 0x3dd53b94, v4
	v_and_b32_e32 v5, 0xffff0000, v11
	v_and_b32_e32 v4, 0xffff0000, v7
	v_pk_mul_f32 v[6:7], v[14:15], v[4:5] op_sel:[1,0] op_sel_hi:[0,1]
	v_pk_mul_f32 v[4:5], v[14:15], v[4:5]
	v_add_f32_e32 v6, v6, v7
	v_sub_f32_e32 v4, v4, v5
	v_cndmask_b32_e64 v4, v6, v4, s[36:37]
	v_mul_f32_e32 v4, 0x3dd53b94, v4
	v_cvt_pk_fp8_f32 v168, v2, v32
	v_cvt_pk_fp8_f32 v169, v16, v10
	s_nop 0
	v_cvt_pk_fp8_f32 v168, v20, v21 op_sel:[0,0,1]
	v_cvt_pk_fp8_f32 v169, v8, v4 op_sel:[0,0,1]
	s_waitcnt vmcnt(0)
; __device__ __forceinline__ float bf_lo(unsigned w) { return __uint_as_float(w << 16); }
; __device__ __forceinline__ float bf_hi(unsigned w) { return __uint_as_float(w & 0xffff0000u); }
; __device__ __forceinline__ void attn_unit(const bf16_t* __restrict__ Qb, const unsigned char* __restrict__ Kn, const unsigned char* __restrict__ Vp, const unsigned char* __restrict__ Kp, ...
;     ...
;     for (int j = 0; j < 4; ++j) {
;       const u32x4 xa = *(const u32x4*)(Qw + 128 + 8 * j), xb = *(const u32x4*)(Qw + 160 + 8 * j);
;       float r_[8];
; #pragma unroll
;       for (int e = 0; e < 8; ++e) { const f32x2 cs = rp[8 * j + e];
;         const unsigned wa = e < 2 ? xa.x : e < 4 ? xa.y : e < 6 ? xa.z : xa.w, wb = e < 2 ? xb.x : e < 4 ? xb.y : e < 6 ? xb.z : xb.w;
;         const float x1 = (e & 1) ? bf_hi(wa) : bf_lo(wa), x2 = (e & 1) ? bf_hi(wb) : bf_lo(wb);
;         r_[e] = QC * (hi ? (x1 * cs.y + x2 * cs.x) : (x1 * cs.x - x2 * cs.y)); }
;       f[2 * j] = (int)pk4_fp8(r_[0], r_[1], r_[2], r_[3]); f[2 * j + 1] = (int)pk4_fp8(r_[4], r_[5], r_[6], r_[7]);
;     }
;     qf[2] = f;
;   }
;   unsigned oK, oP; const unsigned oV = (unsigned)(wid * 1024 + lane * 16);
;   { const int row = 8 * wid + (lane >> 3), c = (lane & 7) ^ ((row >> 1) & 7); oK = (unsigned)(row * LDKN8 + c * 16); }
;   { const int row = 16 * (wid & 3) + (lane >> 2), c = (lane & 3) ^ ((row >> 2) & 3); oP = (unsigned)(row * LDKP8 + c * 16); }
;     ...
;   ISSUE(0, 0); ISSUE(1, KVBLK); ISSUE(2, 2 * KVBLK); ISSUE(3, 3 * KVBLK); ISSUE(4, 4 * KVBLK);
	v_mov_b64_e32 v[4:5], v[136:137]
	v_mov_b64_e32 v[6:7], v[138:139]
	v_mov_b64_e32 v[12:13], v[140:141]
	v_mov_b64_e32 v[14:15], v[142:143]
	v_mov_b64_e32 v[8:9], v[144:145]
	v_mov_b64_e32 v[10:11], v[146:147]
	v_mov_b64_e32 v[16:17], v[172:173]
	v_mov_b64_e32 v[18:19], v[174:175]
	v_mov_b64_e32 v[20:21], v[176:177]
	v_mov_b64_e32 v[22:23], v[178:179]
	v_mov_b64_e32 v[24:25], v[180:181]
	v_mov_b64_e32 v[26:27], v[182:183]
	v_lshlrev_b32_e32 v0, 16, v4
	v_lshlrev_b32_e32 v1, 16, v12
	v_pk_mul_f32 v[30:31], v[24:25], v[0:1] op_sel:[1,0] op_sel_hi:[0,1]
	v_pk_mul_f32 v[0:1], v[24:25], v[0:1]
	v_add_f32_e32 v2, v30, v31
	v_sub_f32_e32 v0, v0, v1
	v_cndmask_b32_e64 v0, v2, v0, s[36:37]
	v_mul_f32_e32 v2, 0x3dd53b94, v0
	v_and_b32_e32 v1, 0xffff0000, v12
	v_and_b32_e32 v0, 0xffff0000, v4
	v_pk_mul_f32 v[24:25], v[26:27], v[0:1] op_sel:[1,0] op_sel_hi:[0,1]
	v_pk_mul_f32 v[0:1], v[26:27], v[0:1]
	v_add_f32_e32 v4, v24, v25
	v_sub_f32_e32 v0, v0, v1
	v_cndmask_b32_e64 v0, v4, v0, s[36:37]
	v_mul_f32_e32 v12, 0x3dd53b94, v0
	v_lshlrev_b32_e32 v1, 16, v13
	v_lshlrev_b32_e32 v0, 16, v5
	v_pk_mul_f32 v[24:25], v[20:21], v[0:1] op_sel:[1,0] op_sel_hi:[0,1]
	v_pk_mul_f32 v[0:1], v[20:21], v[0:1]
	v_add_f32_e32 v4, v24, v25
	v_sub_f32_e32 v0, v0, v1
	v_cndmask_b32_e64 v0, v4, v0, s[36:37]
	v_mul_f32_e32 v20, 0x3dd53b94, v0
	v_and_b32_e32 v1, 0xffff0000, v13
	v_and_b32_e32 v0, 0xffff0000, v5
	v_pk_mul_f32 v[4:5], v[22:23], v[0:1] op_sel:[1,0] op_sel_hi:[0,1]
	v_pk_mul_f32 v[0:1], v[22:23], v[0:1]
	v_add_f32_e32 v4, v4, v5
	v_sub_f32_e32 v0, v0, v1
	v_cndmask_b32_e64 v0, v4, v0, s[36:37]
	v_mul_f32_e32 v13, 0x3dd53b94, v0
	v_lshlrev_b32_e32 v1, 16, v14
	v_lshlrev_b32_e32 v0, 16, v6
	v_pk_mul_f32 v[4:5], v[16:17], v[0:1] op_sel:[1,0] op_sel_hi:[0,1]
	v_pk_mul_f32 v[0:1], v[16:17], v[0:1]
	v_add_f32_e32 v4, v4, v5
	v_sub_f32_e32 v0, v0, v1
	v_cndmask_b32_e64 v0, v4, v0, s[36:37]
	v_mul_f32_e32 v16, 0x3dd53b94, v0
	v_and_b32_e32 v1, 0xffff0000, v14
	v_and_b32_e32 v0, 0xffff0000, v6
	v_pk_mul_f32 v[4:5], v[18:19], v[0:1] op_sel:[1,0] op_sel_hi:[0,1]
	v_pk_mul_f32 v[0:1], v[18:19], v[0:1]
	v_add_f32_e32 v4, v4, v5
	v_sub_f32_e32 v0, v0, v1
	v_cndmask_b32_e64 v0, v4, v0, s[36:37]
	v_mul_f32_e32 v6, 0x3dd53b94, v0
	v_lshlrev_b32_e32 v1, 16, v15
	v_lshlrev_b32_e32 v0, 16, v7
	v_pk_mul_f32 v[4:5], v[8:9], v[0:1] op_sel:[1,0] op_sel_hi:[0,1]
	v_pk_mul_f32 v[0:1], v[8:9], v[0:1]
	v_add_f32_e32 v4, v4, v5
	v_sub_f32_e32 v0, v0, v1
	v_cndmask_b32_e64 v0, v4, v0, s[36:37]
	v_mul_f32_e32 v8, 0x3dd53b94, v0
	v_and_b32_e32 v1, 0xffff0000, v15
	v_and_b32_e32 v0, 0xffff0000, v7
	v_pk_mul_f32 v[4:5], v[10:11], v[0:1] op_sel:[1,0] op_sel_hi:[0,1]
	v_pk_mul_f32 v[0:1], v[10:11], v[0:1]
	v_add_f32_e32 v4, v4, v5
	v_sub_f32_e32 v0, v0, v1
	v_cndmask_b32_e64 v0, v4, v0, s[36:37]
	v_mul_f32_e32 v0, 0x3dd53b94, v0
	v_cvt_pk_fp8_f32 v171, v16, v6
	v_cvt_pk_fp8_f32 v170, v2, v12
	v_or_b32_e32 v2, s9, v54
	v_cvt_pk_fp8_f32 v171, v8, v0 op_sel:[0,0,1]
	v_lshl_or_b32 v0, s2, 3, v55
	v_lshrrev_b32_e32 v1, 1, v0
	v_xor_b32_e32 v1, v1, v28
	v_lshlrev_b32_e32 v1, 4, v1
	v_and_b32_e32 v56, 0x70, v1
	v_lshl_or_b32 v0, v0, 12, v56
	global_load_lds_dwordx4 v2, s[60:61]
	s_add_i32 m0, s8, 0xc000
	s_cmp_lt_i32 s2, 4
	global_load_lds_dwordx4 v0, s[58:59]
	v_mov_b32_e32 v1, v3
	s_cselect_b64 s[28:29], -1, 0
	s_cmp_gt_i32 s2, 3
	s_cselect_b64 s[80:81], -1, 0
	v_lshl_add_u64 v[52:53], s[60:61], 0, v[2:3]
	v_lshl_add_u64 v[0:1], s[58:59], 0, v[0:1]
	s_mov_b64 s[58:59], 0x40000
	s_and_b64 vcc, exec, s[80:81]
	v_lshl_add_u64 v[6:7], v[52:53], 0, s[22:23]
	v_lshl_add_u64 v[4:5], v[0:1], 0, s[58:59]
	v_cvt_pk_fp8_f32 v170, v20, v13 op_sel:[0,0,1]
	s_cbranch_vccz .LBB0_629
	s_add_i32 m0, s8, 0x2000
	s_mov_b64 s[62:63], 0
	global_load_lds_dwordx4 v[6:7], off
